# strategy 4: static s_setprio 1 for workgroups with blockIdx bit 8 during the attention phase
# baseline (speedup 1.0000x reference)
; DI void phase2(const Params& p, u16* smem) {
;   unsigned char* ws = p.ws;
;   const u16* qa = (const u16*)(ws + OFF_QA); const u16* ka = (const u16*)(ws + OFF_KA); const u16* vta = (const u16*)(ws + OFF_VTA);
;   const u16* qb = (const u16*)(ws + OFF_QB); const u16* kb = (const u16*)(ws + OFF_KB); const u16* vtb = (const u16*)(ws + OFF_VTB);
;   u16* oab = (u16*)(ws + OFF_OAB);
;   float* ssq = (float*)(ws + OFF_SSQ);
;   const float cexp = 0.125f * LOG2E;
;   constexpr int NB_S = 2 * 8 * 128, NB_P = 32 * 8 * 16;
;   constexpr int NUNITS = 2 * (NB_S + NB_P);
;   const bool fixedB = ((const float*)(ws + OFF_BOUND))[1] <= 40.0f;
;   if (fixedB) {
;     constexpr int N2_S = 2 * 8 * 64, N2_P = 32 * 8 * 8;
;     for (int u = blockIdx.x; u < N2_S + N2_P; u += gridDim.x) {
.LBB0_227:
	s_or_b64 exec, exec, s[8:9]
	v_mov_b32_e32 v0, 0x2f9f0000
	s_barrier
	s_bitcmp1_b32 s2, 8
	s_cbranch_scc0 .Lprio_skip
	s_setprio 1
.Lprio_skip:
	global_load_dword v0, v0, s[14:15] offset:2052
	s_add_u32 s56, s14, 0xc188000
	s_addc_u32 s57, s15, 0
	s_add_u32 s58, s14, 0x12188000
	s_addc_u32 s59, s15, 0
	s_add_u32 s60, s14, 0x13988000
	s_addc_u32 s61, s15, 0
	s_add_u32 s62, s14, 0x15188000
	s_mov_b32 s8, 0x42200000
	s_addc_u32 s63, s15, 0
	s_add_u32 s64, s14, 0x21188000
	s_addc_u32 s65, s15, 0
	s_waitcnt vmcnt(0)
	v_cmp_nge_f32_e32 vcc, s8, v0
	s_mov_b32 s8, 0
	s_cbranch_vccnz .LBB0_242
	s_cmpk_gt_i32 s2, 0xbff
	s_cbranch_scc1 .LBB0_241
	v_bitop3_b32 v1, v202, v208, 7 bitop3:0x78
	v_bfe_u32 v0, v188, 1, 3
	v_lshlrev_b32_e32 v173, 4, v1
	v_bitop3_b32 v1, v207, v208, 7 bitop3:0x78
	v_lshlrev_b32_e32 v174, 4, v1
	v_bitop3_b32 v1, v202, v0, 4 bitop3:0x36
	v_bitop3_b32 v0, v202, v0, 6 bitop3:0x36
	v_lshlrev_b32_e32 v170, 3, v202
	v_lshrrev_b32_e32 v171, 3, v195
	v_lshlrev_b32_e32 v172, 7, v201
	v_lshlrev_b32_e32 v175, 4, v1
	v_lshlrev_b32_e32 v176, 4, v0
	v_cmp_gt_u32_e64 s[8:9], 32, v195
	v_mov_b32_e32 v165, 0
	s_mov_b64 s[10:11], 0x80
	s_mov_b64 s[20:21], 0x100
	s_mov_b32 s23, 0
	s_mov_b32 s36, s2
	s_branch .LBB0_231

; DI void grid_bar(unsigned* cnt, unsigned& gen) {
;   asm volatile("s_waitcnt vmcnt(0) lgkmcnt(0)" ::: "memory");
;   __syncthreads();
;   gen += 1;
;   if (threadIdx.x == 0) {
;     __builtin_amdgcn_fence(__ATOMIC_RELEASE, "agent");
;     asm volatile("s_waitcnt vmcnt(0)" ::: "memory");
;     __hip_atomic_fetch_add(cnt, 1u, __ATOMIC_RELAXED, __HIP_MEMORY_SCOPE_AGENT);
;     const unsigned target = gen * gridDim.x;
.LBB0_285:
	s_setprio 0
	s_waitcnt vmcnt(0) lgkmcnt(0)
	s_barrier
	s_and_saveexec_b64 s[8:9], s[6:7]
	s_cbranch_execz .LBB0_291
	s_mov_b64 s[10:11], exec
	buffer_wbl2 sc1
	s_waitcnt vmcnt(0)
	v_mbcnt_lo_u32_b32 v0, s10, 0
	v_mbcnt_hi_u32_b32 v0, s11, v0
	v_cmp_eq_u32_e32 vcc, 0, v0
	s_and_saveexec_b64 s[20:21], vcc
	s_cbranch_execz .LBB0_288
	s_bcnt1_i32_b64 s10, s[10:11]
	v_mov_b32_e32 v0, 0
	v_mov_b32_e32 v1, s10
	global_atomic_add v0, v1, s[18:19]
